# LayerNorm and ssd_post wave sums: six ds_bpermute round trips replaced by DPP row adds plus permlane16/32_swap exchanges (f32 adds, no LDS latency)
# speedup vs baseline: 1.0134x; 1.0018x over previous
; DI unsigned pack2(float a, float b) { f32x2_t v = {a, b}; return __builtin_bit_cast(unsigned, __builtin_convertvector(v, bf16x2_t)); }
; DI float lo2f(unsigned v) { return __uint_as_float(v << 16); }
; DI float hi2f(unsigned v) { return __uint_as_float(v & 0xffff0000u); }
; DI float wave_sum(float v) { for (int o = 32; o >= 1; o >>= 1) v += __shfl_xor(v, o); return v; }
; DI void ln_phase(int wvs, bf16_t* HB, const float* __restrict__ g, const float* __restrict__ bta, float* fout, bool dostore = true) {
;   const int tid = opaque_tid(wvs);
;   const int lane = tid & 63, w = tid >> 6;
;   for (int row = blockIdx.x * 8 + w; row < MTOT; row += gridDim.x * 8) {
;     bf16_t* p = HB + (size_t)row * 1024;
;     float v[16];
;     float s = 0.f;
; #pragma unroll
;     for (int i = 0; i < 2; ++i) {
;       const u32x4 raw = *(const u32x4*)(p + i * 512 + lane * 8);
; #pragma unroll
;       for (int j = 0; j < 4; ++j) { v[i * 8 + 2 * j] = lo2f(raw[j]); v[i * 8 + 2 * j + 1] = hi2f(raw[j]); }
;     }
; #pragma unroll
;     for (int i = 0; i < 16; ++i) s += v[i];
;     const float mean = wave_sum(s) * (1.f / 1024.f);
;     float q = 0.f;
; #pragma unroll
;     for (int i = 0; i < 16; ++i) { v[i] -= mean; q += v[i] * v[i]; }
;     const float rstd = rsqrtf(wave_sum(q) * (1.f / 1024.f) + 1e-5f);
; #pragma unroll
;     for (int i = 0; i < 2; ++i) {
;       const int c = i * 512 + lane * 8;
;       const float4 g0 = *(const float4*)(g + c), g1 = *(const float4*)(g + c + 4), b0 = *(const float4*)(bta + c), b1 = *(const float4*)(bta + c + 4);
;       float o[8];
;       o[0] = v[i * 8 + 0] * rstd * g0.x + b0.x; o[1] = v[i * 8 + 1] * rstd * g0.y + b0.y; o[2] = v[i * 8 + 2] * rstd * g0.z + b0.z; o[3] = v[i * 8 + 3] * rstd * g0.w + b0.w;
;       o[4] = v[i * 8 + 4] * rstd * g1.x + b1.x; o[5] = v[i * 8 + 5] * rstd * g1.y + b1.y; o[6] = v[i * 8 + 6] * rstd * g1.z + b1.z; o[7] = v[i * 8 + 7] * rstd * g1.w + b1.w;
;       if (dostore) {
;         u32x4 pk; pk[0] = pack2(o[0], o[1]); pk[1] = pack2(o[2], o[3]); pk[2] = pack2(o[4], o[5]); pk[3] = pack2(o[6], o[7]);
;         *(u32x4*)(p + c) = pk;
.LBB0_499:
	v_ashrrev_i32_e32 v33, 31, v32
	v_lshlrev_b64 v[36:37], 11, v[32:33]
	v_lshl_add_u64 v[36:37], v[34:35], 0, v[36:37]
	global_load_dwordx4 v[44:47], v[36:37], off
	global_load_dwordx4 v[48:51], v[36:37], off offset:1024
	v_add_u32_e32 v32, s13, v32
	s_waitcnt vmcnt(1)
	v_lshlrev_b32_e32 v56, 16, v44
	v_and_b32_e32 v57, 0xffff0000, v44
	v_add_f32_e32 v33, 0, v56
	v_lshlrev_b32_e32 v54, 16, v46
	v_and_b32_e32 v55, 0xffff0000, v46
	v_lshlrev_b32_e32 v46, 16, v45
	v_add_f32_e32 v33, v33, v57
	v_lshlrev_b32_e32 v52, 16, v47
	v_and_b32_e32 v53, 0xffff0000, v47
	v_and_b32_e32 v47, 0xffff0000, v45
	v_add_f32_e32 v33, v33, v46
	v_add_f32_e32 v33, v33, v47
	v_add_f32_e32 v33, v33, v54
	v_add_f32_e32 v33, v33, v55
	v_add_f32_e32 v33, v33, v52
	v_add_f32_e32 v33, v33, v53
	s_waitcnt vmcnt(0)
	v_lshlrev_b32_e32 v60, 16, v48
	v_and_b32_e32 v61, 0xffff0000, v48
	v_add_f32_e32 v33, v33, v60
	v_lshlrev_b32_e32 v58, 16, v50
	v_and_b32_e32 v59, 0xffff0000, v50
	v_lshlrev_b32_e32 v50, 16, v49
	v_add_f32_e32 v33, v33, v61
	v_lshlrev_b32_e32 v44, 16, v51
	v_and_b32_e32 v45, 0xffff0000, v51
	v_and_b32_e32 v51, 0xffff0000, v49
	v_add_f32_e32 v33, v33, v50
	v_add_f32_e32 v33, v33, v51
	v_add_f32_e32 v33, v33, v58
	v_add_f32_e32 v33, v33, v59
	v_add_f32_e32 v33, v33, v44
	v_add_f32_e32 v33, v33, v45
	s_nop 1
	v_add_f32_dpp v33, v33, v33 quad_perm:[1,0,3,2] row_mask:0xf bank_mask:0xf
	s_nop 1
	v_add_f32_dpp v33, v33, v33 quad_perm:[2,3,0,1] row_mask:0xf bank_mask:0xf
	s_nop 1
	v_add_f32_dpp v33, v33, v33 row_half_mirror row_mask:0xf bank_mask:0xf
	s_nop 1
	v_add_f32_dpp v33, v33, v33 row_mirror row_mask:0xf bank_mask:0xf
	v_mov_b32_e32 v48, v33
	s_nop 1
	v_permlane16_swap_b32_e32 v48, v33
	v_add_f32_e32 v33, v33, v48
	v_mov_b32_e32 v48, v33
	s_nop 1
	v_permlane32_swap_b32_e32 v48, v33
	v_add_f32_e32 v33, v33, v48
	v_mul_f32_e32 v48, 0x3a800000, v33
	v_pk_add_f32 v[56:57], v[56:57], v[48:49] op_sel_hi:[1,0] neg_lo:[0,1] neg_hi:[0,1]
	v_pk_add_f32 v[46:47], v[46:47], v[48:49] op_sel_hi:[1,0] neg_lo:[0,1] neg_hi:[0,1]
	v_pk_mul_f32 v[62:63], v[56:57], v[56:57]
	v_pk_mul_f32 v[64:65], v[46:47], v[46:47]
	v_add_f32_e32 v33, v62, v63
	v_pk_add_f32 v[54:55], v[54:55], v[48:49] op_sel_hi:[1,0] neg_lo:[0,1] neg_hi:[0,1]
	v_add_f32_e32 v33, v64, v33
	v_pk_mul_f32 v[66:67], v[54:55], v[54:55]
	v_add_f32_e32 v33, v65, v33
	v_pk_add_f32 v[52:53], v[52:53], v[48:49] op_sel_hi:[1,0] neg_lo:[0,1] neg_hi:[0,1]
	v_add_f32_e32 v33, v66, v33
	v_pk_mul_f32 v[68:69], v[52:53], v[52:53]
	v_add_f32_e32 v33, v67, v33
	v_pk_add_f32 v[60:61], v[60:61], v[48:49] op_sel_hi:[1,0] neg_lo:[0,1] neg_hi:[0,1]
	v_add_f32_e32 v33, v68, v33
	v_pk_mul_f32 v[70:71], v[60:61], v[60:61]
	v_add_f32_e32 v33, v69, v33
	v_pk_add_f32 v[50:51], v[50:51], v[48:49] op_sel_hi:[1,0] neg_lo:[0,1] neg_hi:[0,1]
	v_add_f32_e32 v33, v70, v33
	v_pk_mul_f32 v[72:73], v[50:51], v[50:51]
	v_add_f32_e32 v33, v71, v33
	v_pk_add_f32 v[58:59], v[58:59], v[48:49] op_sel_hi:[1,0] neg_lo:[0,1] neg_hi:[0,1]
	v_add_f32_e32 v33, v72, v33
	v_pk_mul_f32 v[74:75], v[58:59], v[58:59]
	v_add_f32_e32 v33, v73, v33
	v_pk_add_f32 v[48:49], v[44:45], v[48:49] op_sel_hi:[1,0] neg_lo:[0,1] neg_hi:[0,1]
	v_add_f32_e32 v33, v74, v33
	v_pk_mul_f32 v[44:45], v[48:49], v[48:49]
	v_add_f32_e32 v33, v75, v33
	v_add_f32_e32 v33, v44, v33
	v_add_f32_e32 v33, v45, v33
	s_nop 1
	v_add_f32_dpp v33, v33, v33 quad_perm:[1,0,3,2] row_mask:0xf bank_mask:0xf
	s_nop 1
	v_add_f32_dpp v33, v33, v33 quad_perm:[2,3,0,1] row_mask:0xf bank_mask:0xf
	s_nop 1
	v_add_f32_dpp v33, v33, v33 row_half_mirror row_mask:0xf bank_mask:0xf
	s_nop 1
	v_add_f32_dpp v33, v33, v33 row_mirror row_mask:0xf bank_mask:0xf
	v_mov_b32_e32 v44, v33
	s_nop 1
	v_permlane16_swap_b32_e32 v44, v33
	v_add_f32_e32 v33, v33, v44
	v_mov_b32_e32 v44, v33
	s_nop 1
	v_permlane32_swap_b32_e32 v44, v33
	v_add_f32_e32 v33, v33, v44
	v_fmamk_f32 v33, v33, 0x3a800000, v177
	v_cmp_gt_f32_e32 vcc, s75, v33
	v_mul_f32_e32 v44, 0x4b800000, v33
	s_nop 0
	v_cndmask_b32_e32 v33, v33, v44, vcc
	v_rsq_f32_e32 v33, v33
	s_nop 0
	v_mul_f32_e32 v44, 0x45800000, v33
	v_cndmask_b32_e32 v62, v33, v44, vcc
	v_pk_mul_f32 v[44:45], v[56:57], v[62:63] op_sel_hi:[1,0]
	v_pk_mul_f32 v[46:47], v[46:47], v[62:63] op_sel_hi:[1,0]
	v_pk_mul_f32 v[54:55], v[54:55], v[62:63] op_sel_hi:[1,0]
	v_pk_mul_f32 v[52:53], v[52:53], v[62:63] op_sel_hi:[1,0]
	v_pk_fma_f32 v[44:45], v[4:5], v[44:45], v[12:13]
	v_pk_fma_f32 v[46:47], v[6:7], v[46:47], v[14:15]
	v_pk_fma_f32 v[54:55], v[0:1], v[54:55], v[8:9]
	v_pk_fma_f32 v[52:53], v[2:3], v[52:53], v[10:11]
	v_cvt_pk_bf16_f32 v44, v44, v45
	v_cvt_pk_bf16_f32 v45, v46, v47
	v_cvt_pk_bf16_f32 v46, v54, v55
	v_cvt_pk_bf16_f32 v47, v52, v53
	global_store_dwordx4 v[36:37], v[44:47], off
	v_pk_mul_f32 v[48:49], v[48:49], v[62:63] op_sel_hi:[1,0]
	v_cmp_lt_i32_e32 vcc, s76, v32
	v_pk_mul_f32 v[44:45], v[60:61], v[62:63] op_sel_hi:[1,0]
	v_pk_mul_f32 v[46:47], v[50:51], v[62:63] op_sel_hi:[1,0]
	v_pk_mul_f32 v[50:51], v[58:59], v[62:63] op_sel_hi:[1,0]
	v_pk_fma_f32 v[44:45], v[20:21], v[44:45], v[28:29]
	v_pk_fma_f32 v[46:47], v[22:23], v[46:47], v[30:31]
	v_pk_fma_f32 v[50:51], v[16:17], v[50:51], v[24:25]
	v_pk_fma_f32 v[48:49], v[18:19], v[48:49], v[26:27]
	v_cvt_pk_bf16_f32 v44, v44, v45
	v_cvt_pk_bf16_f32 v45, v46, v47
	v_cvt_pk_bf16_f32 v46, v50, v51
	v_cvt_pk_bf16_f32 v47, v48, v49
	s_or_b64 s[42:43], vcc, s[42:43]
	global_store_dwordx4 v[36:37], v[44:47], off offset:1024
	s_andn2_b64 exec, exec, s[42:43]
	s_cbranch_execnz .LBB0_499

; DI unsigned pack2(float a, float b) { f32x2_t v = {a, b}; return __builtin_bit_cast(unsigned, __builtin_convertvector(v, bf16x2_t)); }
; DI float lo2f(unsigned v) { return __uint_as_float(v << 16); }
; DI float hi2f(unsigned v) { return __uint_as_float(v & 0xffff0000u); }
; DI float silu(float x) { return x * __builtin_amdgcn_rcpf(1.f + __expf(-x)); }
; DI float wave_sum(float v) { for (int o = 32; o >= 1; o >>= 1) v += __shfl_xor(v, o); return v; }
; DI void ssd_post_phase(int wvs, const bf16_t* __restrict__ PROJ, const bf16_t* __restrict__ XBC, bf16_t* YF, const bf16_t* __restrict__ YB,
;                        const float* __restrict__ d_skip, const float* __restrict__ norm_g, bool dostore = true) {
;   const int tid = opaque_tid(wvs);
;   const int lane = tid & 63, w = tid >> 6;
;   for (int itw = blockIdx.x * 8 + w; itw < MH * 4; itw += gridDim.x * 8) {
;     const int m = itw >> 2, grp = itw & 3, col = grp * 512 + lane * 8;
;     const u32x4 yf = *(const u32x4*)(YF + (size_t)m * 2048 + col);
;     const u32x4 yb = *(const u32x4*)(YB + (size_t)m * 2048 + col);
;     const u32x4 xs = *(const u32x4*)(XBC + (size_t)m * 3072 + col);
;     const u32x4 zz = *(const u32x4*)(PROJ + (size_t)m * 5248 + col);
;     const float dsk = d_skip[col >> 6];
;     float v[8];
;     float ss = 0.f;
; #pragma unroll
;     for (int j = 0; j < 4; ++j) {
;       v[2 * j] = (lo2f(yf[j]) + lo2f(yb[j]) + lo2f(xs[j]) * dsk) * silu(lo2f(zz[j]));
;       v[2 * j + 1] = (hi2f(yf[j]) + hi2f(yb[j]) + hi2f(xs[j]) * dsk) * silu(hi2f(zz[j]));
;       ss += v[2 * j] * v[2 * j] + v[2 * j + 1] * v[2 * j + 1];
;     }
;     const float sc = rsqrtf(wave_sum(ss) * (1.f / 512.f) + 1e-5f);
;     const float4 g0 = *(const float4*)(norm_g + col), g1 = *(const float4*)(norm_g + col + 4);
;     u32x4 o;
;     o[0] = pack2(v[0] * sc * g0.x, v[1] * sc * g0.y); o[1] = pack2(v[2] * sc * g0.z, v[3] * sc * g0.w);
;     o[2] = pack2(v[4] * sc * g1.x, v[5] * sc * g1.y); o[3] = pack2(v[6] * sc * g1.z, v[7] * sc * g1.w);
;     if (dostore) *(u32x4*)(YF + (size_t)m * 2048 + col) = o;
;   }
.LBB0_973:
	v_ashrrev_i32_e32 v22, 2, v0
	v_ashrrev_i32_e32 v23, 31, v22
	v_and_or_b32 v9, v8, s22, v1
	v_lshlrev_b64 v[14:15], 12, v[22:23]
	v_mov_b64_e32 v[18:19], s[36:37]
	v_mov_b64_e32 v[24:25], s[30:31]
	v_lshl_add_u64 v[10:11], s[12:13], 0, v[14:15]
	v_lshlrev_b32_e32 v128, 1, v9
	v_mad_i64_i32 v[18:19], s[6:7], v22, s5, v[18:19]
	v_mad_i64_i32 v[22:23], s[6:7], v22, s24, v[24:25]
	v_lshl_add_u64 v[34:35], v[10:11], 0, v[128:129]
	v_lshl_add_u64 v[22:23], v[22:23], 0, v[128:129]
	global_load_dwordx4 v[10:13], v[34:35], off
	v_lshl_add_u64 v[14:15], s[68:69], 0, v[14:15]
	global_load_dwordx4 v[22:25], v[22:23], off
	v_lshl_add_u64 v[14:15], v[14:15], 0, v[128:129]
	global_load_dwordx4 v[14:17], v[14:15], off
	v_lshl_add_u64 v[18:19], v[18:19], 0, v[128:129]
	v_lshrrev_b32_e32 v26, 4, v9
	global_load_dwordx4 v[18:21], v[18:19], off
	v_and_b32_e32 v26, 0x7c, v26
	global_load_dword v36, v26, s[58:59]
	v_lshlrev_b32_e32 v9, 2, v9
	v_add_u32_e32 v0, s8, v0
	v_add_u32_e32 v8, s9, v8
	s_waitcnt vmcnt(4)
	v_lshlrev_b32_e32 v30, 16, v13
	v_and_b32_e32 v31, 0xffff0000, v13
	s_waitcnt vmcnt(3)
	v_lshlrev_b32_e32 v26, 16, v25
	v_and_b32_e32 v27, 0xffff0000, v25
	v_mul_f32_e32 v25, 0xbfb8aa3b, v26
	v_mul_f32_e32 v13, 0xbfb8aa3b, v27
	v_exp_f32_e32 v25, v25
	v_exp_f32_e32 v13, v13
	s_waitcnt vmcnt(2)
	v_lshlrev_b32_e32 v32, 16, v17
	v_and_b32_e32 v33, 0xffff0000, v17
	v_add_f32_e32 v25, 1.0, v25
	v_add_f32_e32 v13, 1.0, v13
	v_rcp_f32_e32 v28, v25
	v_rcp_f32_e32 v29, v13
	v_pk_add_f32 v[30:31], v[30:31], v[32:33]
	s_waitcnt vmcnt(1)
	v_lshlrev_b32_e32 v32, 16, v21
	v_and_b32_e32 v33, 0xffff0000, v21
	s_waitcnt vmcnt(0)
	v_pk_fma_f32 v[30:31], v[36:37], v[32:33], v[30:31] op_sel_hi:[0,1,1]
	v_pk_mul_f32 v[26:27], v[28:29], v[26:27]
	v_lshlrev_b32_e32 v40, 16, v24
	v_pk_mul_f32 v[38:39], v[30:31], v[26:27]
	global_load_dwordx4 v[26:29], v9, s[76:77] offset:16
	global_load_dwordx4 v[30:33], v9, s[76:77]
	v_mul_f32_e32 v9, 0xbfb8aa3b, v40
	v_exp_f32_e32 v9, v9
	v_and_b32_e32 v41, 0xffff0000, v24
	v_lshlrev_b32_e32 v42, 16, v12
	v_and_b32_e32 v43, 0xffff0000, v12
	v_add_f32_e32 v9, 1.0, v9
	v_rcp_f32_e32 v24, v9
	v_mul_f32_e32 v9, 0xbfb8aa3b, v41
	v_exp_f32_e32 v9, v9
	v_lshlrev_b32_e32 v12, 16, v16
	v_and_b32_e32 v13, 0xffff0000, v16
	v_pk_add_f32 v[12:13], v[42:43], v[12:13]
	v_add_f32_e32 v9, 1.0, v9
	v_rcp_f32_e32 v25, v9
	v_lshlrev_b32_e32 v16, 16, v20
	v_and_b32_e32 v17, 0xffff0000, v20
	v_pk_fma_f32 v[12:13], v[36:37], v[16:17], v[12:13] op_sel_hi:[0,1,1]
	v_pk_mul_f32 v[16:17], v[24:25], v[40:41]
	v_mov_b32_e32 v20, v39
	v_pk_mul_f32 v[12:13], v[12:13], v[16:17]
	v_mov_b32_e32 v16, v38
	v_mov_b32_e32 v17, v12
	v_pk_mul_f32 v[16:17], v[16:17], v[16:17]
	v_mov_b32_e32 v21, v13
	v_pk_fma_f32 v[16:17], v[20:21], v[20:21], v[16:17]
	v_lshlrev_b32_e32 v20, 16, v23
	v_mul_f32_e32 v9, 0xbfb8aa3b, v20
	v_exp_f32_e32 v9, v9
	v_and_b32_e32 v21, 0xffff0000, v23
	v_lshlrev_b32_e32 v40, 16, v11
	v_and_b32_e32 v41, 0xffff0000, v11
	v_add_f32_e32 v9, 1.0, v9
	v_rcp_f32_e32 v24, v9
	v_mul_f32_e32 v9, 0xbfb8aa3b, v21
	v_exp_f32_e32 v9, v9
	v_lshlrev_b32_e32 v42, 16, v15
	v_and_b32_e32 v43, 0xffff0000, v15
	v_pk_add_f32 v[40:41], v[40:41], v[42:43]
	v_add_f32_e32 v9, 1.0, v9
	v_rcp_f32_e32 v25, v9
	v_lshlrev_b32_e32 v42, 16, v19
	v_and_b32_e32 v43, 0xffff0000, v19
	v_pk_fma_f32 v[40:41], v[36:37], v[42:43], v[40:41] op_sel_hi:[0,1,1]
	v_pk_mul_f32 v[20:21], v[24:25], v[20:21]
	v_lshlrev_b32_e32 v24, 16, v22
	v_mul_f32_e32 v9, 0xbfb8aa3b, v24
	v_exp_f32_e32 v9, v9
	v_and_b32_e32 v25, 0xffff0000, v22
	v_pk_mul_f32 v[20:21], v[40:41], v[20:21]
	v_lshlrev_b32_e32 v40, 16, v10
	v_add_f32_e32 v9, 1.0, v9
	v_rcp_f32_e32 v22, v9
	v_mul_f32_e32 v9, 0xbfb8aa3b, v25
	v_exp_f32_e32 v9, v9
	v_and_b32_e32 v41, 0xffff0000, v10
	v_lshlrev_b32_e32 v10, 16, v14
	v_and_b32_e32 v11, 0xffff0000, v14
	v_add_f32_e32 v9, 1.0, v9
	v_rcp_f32_e32 v23, v9
	v_pk_add_f32 v[10:11], v[40:41], v[10:11]
	v_lshlrev_b32_e32 v14, 16, v18
	v_and_b32_e32 v15, 0xffff0000, v18
	v_pk_fma_f32 v[10:11], v[36:37], v[14:15], v[10:11] op_sel_hi:[0,1,1]
	v_pk_mul_f32 v[14:15], v[22:23], v[24:25]
	v_mov_b32_e32 v19, v21
	v_pk_mul_f32 v[10:11], v[10:11], v[14:15]
	v_mov_b32_e32 v15, v20
	v_mov_b32_e32 v14, v10
	v_pk_mul_f32 v[14:15], v[14:15], v[14:15]
	v_mov_b32_e32 v18, v11
	v_pk_fma_f32 v[14:15], v[18:19], v[18:19], v[14:15]
	s_nop 0
	v_add_f32_e32 v9, v14, v15
	v_add_f32_e32 v9, v17, v9
	v_add_f32_e32 v9, v16, v9
	s_nop 1
	v_add_f32_dpp v9, v9, v9 quad_perm:[1,0,3,2] row_mask:0xf bank_mask:0xf
	s_nop 1
	v_add_f32_dpp v9, v9, v9 quad_perm:[2,3,0,1] row_mask:0xf bank_mask:0xf
	s_nop 1
	v_add_f32_dpp v9, v9, v9 row_half_mirror row_mask:0xf bank_mask:0xf
	s_nop 1
	v_add_f32_dpp v9, v9, v9 row_mirror row_mask:0xf bank_mask:0xf
	v_mov_b32_e32 v14, v9
	s_nop 1
	v_permlane16_swap_b32_e32 v14, v9
	v_add_f32_e32 v9, v9, v14
	v_mov_b32_e32 v14, v9
	s_nop 1
	v_permlane32_swap_b32_e32 v14, v9
	v_add_f32_e32 v9, v9, v14
	v_fmamk_f32 v9, v9, 0x3b000000, v177
	v_cmp_gt_f32_e32 vcc, s75, v9
	v_mul_f32_e32 v14, 0x4b800000, v9
	s_nop 0
	v_cndmask_b32_e32 v9, v9, v14, vcc
	v_rsq_f32_e32 v9, v9
	s_nop 0
	v_mul_f32_e32 v14, 0x45800000, v9
	v_cndmask_b32_e32 v14, v9, v14, vcc
	v_pk_mul_f32 v[10:11], v[10:11], v[14:15] op_sel_hi:[1,0]
	v_pk_mul_f32 v[16:17], v[20:21], v[14:15] op_sel_hi:[1,0]
	v_pk_mul_f32 v[12:13], v[12:13], v[14:15] op_sel_hi:[1,0]
	v_pk_mul_f32 v[14:15], v[38:39], v[14:15] op_sel_hi:[1,0]
	s_waitcnt vmcnt(0)
	v_pk_mul_f32 v[10:11], v[30:31], v[10:11]
	v_pk_mul_f32 v[16:17], v[32:33], v[16:17]
	v_pk_mul_f32 v[12:13], v[26:27], v[12:13]
	v_pk_mul_f32 v[14:15], v[28:29], v[14:15]
	v_cmp_lt_i32_e32 vcc, s23, v0
	v_cvt_pk_bf16_f32 v10, v10, v11
	v_cvt_pk_bf16_f32 v11, v16, v17
	v_cvt_pk_bf16_f32 v12, v12, v13
	v_cvt_pk_bf16_f32 v13, v14, v15
	s_or_b64 s[42:43], vcc, s[42:43]
	global_store_dwordx4 v[34:35], v[10:13], off
	s_andn2_b64 exec, exec, s[42:43]
	s_cbranch_execnz .LBB0_973

; DI unsigned pack2(float a, float b) { f32x2_t v = {a, b}; return __builtin_bit_cast(unsigned, __builtin_convertvector(v, bf16x2_t)); }
; DI float lo2f(unsigned v) { return __uint_as_float(v << 16); }
; DI float hi2f(unsigned v) { return __uint_as_float(v & 0xffff0000u); }
; DI float wave_sum(float v) { for (int o = 32; o >= 1; o >>= 1) v += __shfl_xor(v, o); return v; }
; DI void ln_phase(int wvs, bf16_t* HB, const float* __restrict__ g, const float* __restrict__ bta, float* fout, bool dostore = true) {
;   const int tid = opaque_tid(wvs);
;   const int lane = tid & 63, w = tid >> 6;
;   for (int row = blockIdx.x * 8 + w; row < MTOT; row += gridDim.x * 8) {
;     bf16_t* p = HB + (size_t)row * 1024;
;     float v[16];
;     float s = 0.f;
; #pragma unroll
;     for (int i = 0; i < 2; ++i) {
;       const u32x4 raw = *(const u32x4*)(p + i * 512 + lane * 8);
; #pragma unroll
;       for (int j = 0; j < 4; ++j) { v[i * 8 + 2 * j] = lo2f(raw[j]); v[i * 8 + 2 * j + 1] = hi2f(raw[j]); }
;     }
; #pragma unroll
;     for (int i = 0; i < 16; ++i) s += v[i];
;     const float mean = wave_sum(s) * (1.f / 1024.f);
;     float q = 0.f;
; #pragma unroll
;     for (int i = 0; i < 16; ++i) { v[i] -= mean; q += v[i] * v[i]; }
;     const float rstd = rsqrtf(wave_sum(q) * (1.f / 1024.f) + 1e-5f);
; #pragma unroll
;     for (int i = 0; i < 2; ++i) {
;       const int c = i * 512 + lane * 8;
;       const float4 g0 = *(const float4*)(g + c), g1 = *(const float4*)(g + c + 4), b0 = *(const float4*)(bta + c), b1 = *(const float4*)(bta + c + 4);
;       float o[8];
;       o[0] = v[i * 8 + 0] * rstd * g0.x + b0.x; o[1] = v[i * 8 + 1] * rstd * g0.y + b0.y; o[2] = v[i * 8 + 2] * rstd * g0.z + b0.z; o[3] = v[i * 8 + 3] * rstd * g0.w + b0.w;
;       o[4] = v[i * 8 + 4] * rstd * g1.x + b1.x; o[5] = v[i * 8 + 5] * rstd * g1.y + b1.y; o[6] = v[i * 8 + 6] * rstd * g1.z + b1.z; o[7] = v[i * 8 + 7] * rstd * g1.w + b1.w;
;       if (dostore) {
;         u32x4 pk; pk[0] = pack2(o[0], o[1]); pk[1] = pack2(o[2], o[3]); pk[2] = pack2(o[4], o[5]); pk[3] = pack2(o[6], o[7]);
;         *(u32x4*)(p + c) = pk;
.LBB0_1027:
	v_ashrrev_i32_e32 v33, 31, v32
	v_lshlrev_b64 v[36:37], 11, v[32:33]
	v_lshl_add_u64 v[36:37], v[34:35], 0, v[36:37]
	global_load_dwordx4 v[44:47], v[36:37], off
	global_load_dwordx4 v[48:51], v[36:37], off offset:1024
	v_add_u32_e32 v32, s13, v32
	s_waitcnt vmcnt(1)
	v_lshlrev_b32_e32 v56, 16, v44
	v_and_b32_e32 v57, 0xffff0000, v44
	v_add_f32_e32 v33, 0, v56
	v_lshlrev_b32_e32 v54, 16, v46
	v_and_b32_e32 v55, 0xffff0000, v46
	v_lshlrev_b32_e32 v46, 16, v45
	v_add_f32_e32 v33, v33, v57
	v_lshlrev_b32_e32 v52, 16, v47
	v_and_b32_e32 v53, 0xffff0000, v47
	v_and_b32_e32 v47, 0xffff0000, v45
	v_add_f32_e32 v33, v33, v46
	v_add_f32_e32 v33, v33, v47
	v_add_f32_e32 v33, v33, v54
	v_add_f32_e32 v33, v33, v55
	v_add_f32_e32 v33, v33, v52
	v_add_f32_e32 v33, v33, v53
	s_waitcnt vmcnt(0)
	v_lshlrev_b32_e32 v60, 16, v48
	v_and_b32_e32 v61, 0xffff0000, v48
	v_add_f32_e32 v33, v33, v60
	v_lshlrev_b32_e32 v58, 16, v50
	v_and_b32_e32 v59, 0xffff0000, v50
	v_lshlrev_b32_e32 v50, 16, v49
	v_add_f32_e32 v33, v33, v61
	v_lshlrev_b32_e32 v44, 16, v51
	v_and_b32_e32 v45, 0xffff0000, v51
	v_and_b32_e32 v51, 0xffff0000, v49
	v_add_f32_e32 v33, v33, v50
	v_add_f32_e32 v33, v33, v51
	v_add_f32_e32 v33, v33, v58
	v_add_f32_e32 v33, v33, v59
	v_add_f32_e32 v33, v33, v44
	v_add_f32_e32 v33, v33, v45
	s_nop 1
	v_add_f32_dpp v33, v33, v33 quad_perm:[1,0,3,2] row_mask:0xf bank_mask:0xf
	s_nop 1
	v_add_f32_dpp v33, v33, v33 quad_perm:[2,3,0,1] row_mask:0xf bank_mask:0xf
	s_nop 1
	v_add_f32_dpp v33, v33, v33 row_half_mirror row_mask:0xf bank_mask:0xf
	s_nop 1
	v_add_f32_dpp v33, v33, v33 row_mirror row_mask:0xf bank_mask:0xf
	v_mov_b32_e32 v48, v33
	s_nop 1
	v_permlane16_swap_b32_e32 v48, v33
	v_add_f32_e32 v33, v33, v48
	v_mov_b32_e32 v48, v33
	s_nop 1
	v_permlane32_swap_b32_e32 v48, v33
	v_add_f32_e32 v33, v33, v48
	v_mul_f32_e32 v48, 0x3a800000, v33
	v_pk_add_f32 v[56:57], v[56:57], v[48:49] op_sel_hi:[1,0] neg_lo:[0,1] neg_hi:[0,1]
	v_pk_add_f32 v[46:47], v[46:47], v[48:49] op_sel_hi:[1,0] neg_lo:[0,1] neg_hi:[0,1]
	v_pk_mul_f32 v[62:63], v[56:57], v[56:57]
	v_pk_mul_f32 v[64:65], v[46:47], v[46:47]
	v_add_f32_e32 v33, v62, v63
	v_pk_add_f32 v[54:55], v[54:55], v[48:49] op_sel_hi:[1,0] neg_lo:[0,1] neg_hi:[0,1]
	v_add_f32_e32 v33, v64, v33
	v_pk_mul_f32 v[66:67], v[54:55], v[54:55]
	v_add_f32_e32 v33, v65, v33
	v_pk_add_f32 v[52:53], v[52:53], v[48:49] op_sel_hi:[1,0] neg_lo:[0,1] neg_hi:[0,1]
	v_add_f32_e32 v33, v66, v33
	v_pk_mul_f32 v[68:69], v[52:53], v[52:53]
	v_add_f32_e32 v33, v67, v33
	v_pk_add_f32 v[60:61], v[60:61], v[48:49] op_sel_hi:[1,0] neg_lo:[0,1] neg_hi:[0,1]
	v_add_f32_e32 v33, v68, v33
	v_pk_mul_f32 v[70:71], v[60:61], v[60:61]
	v_add_f32_e32 v33, v69, v33
	v_pk_add_f32 v[50:51], v[50:51], v[48:49] op_sel_hi:[1,0] neg_lo:[0,1] neg_hi:[0,1]
	v_add_f32_e32 v33, v70, v33
	v_pk_mul_f32 v[72:73], v[50:51], v[50:51]
	v_add_f32_e32 v33, v71, v33
	v_pk_add_f32 v[58:59], v[58:59], v[48:49] op_sel_hi:[1,0] neg_lo:[0,1] neg_hi:[0,1]
	v_add_f32_e32 v33, v72, v33
	v_pk_mul_f32 v[74:75], v[58:59], v[58:59]
	v_add_f32_e32 v33, v73, v33
	v_pk_add_f32 v[48:49], v[44:45], v[48:49] op_sel_hi:[1,0] neg_lo:[0,1] neg_hi:[0,1]
	v_add_f32_e32 v33, v74, v33
	v_pk_mul_f32 v[44:45], v[48:49], v[48:49]
	v_add_f32_e32 v33, v75, v33
	v_add_f32_e32 v33, v44, v33
	v_add_f32_e32 v33, v45, v33
	s_nop 1
	v_add_f32_dpp v33, v33, v33 quad_perm:[1,0,3,2] row_mask:0xf bank_mask:0xf
	s_nop 1
	v_add_f32_dpp v33, v33, v33 quad_perm:[2,3,0,1] row_mask:0xf bank_mask:0xf
	s_nop 1
	v_add_f32_dpp v33, v33, v33 row_half_mirror row_mask:0xf bank_mask:0xf
	s_nop 1
	v_add_f32_dpp v33, v33, v33 row_mirror row_mask:0xf bank_mask:0xf
	v_mov_b32_e32 v44, v33
	s_nop 1
	v_permlane16_swap_b32_e32 v44, v33
	v_add_f32_e32 v33, v33, v44
	v_mov_b32_e32 v44, v33
	s_nop 1
	v_permlane32_swap_b32_e32 v44, v33
	v_add_f32_e32 v33, v33, v44
	v_fmamk_f32 v33, v33, 0x3a800000, v177
	v_cmp_gt_f32_e32 vcc, s75, v33
	v_mul_f32_e32 v44, 0x4b800000, v33
	s_nop 0
	v_cndmask_b32_e32 v33, v33, v44, vcc
	v_rsq_f32_e32 v33, v33
	s_nop 0
	v_mul_f32_e32 v44, 0x45800000, v33
	v_cndmask_b32_e32 v62, v33, v44, vcc
	v_pk_mul_f32 v[44:45], v[56:57], v[62:63] op_sel_hi:[1,0]
	v_pk_mul_f32 v[46:47], v[46:47], v[62:63] op_sel_hi:[1,0]
	v_pk_mul_f32 v[54:55], v[54:55], v[62:63] op_sel_hi:[1,0]
	v_pk_mul_f32 v[52:53], v[52:53], v[62:63] op_sel_hi:[1,0]
	v_pk_fma_f32 v[44:45], v[8:9], v[44:45], v[12:13]
	v_pk_fma_f32 v[46:47], v[10:11], v[46:47], v[14:15]
	v_pk_fma_f32 v[54:55], v[0:1], v[54:55], v[4:5]
	v_pk_fma_f32 v[52:53], v[2:3], v[52:53], v[6:7]
	v_cvt_pk_bf16_f32 v44, v44, v45
	v_cvt_pk_bf16_f32 v45, v46, v47
	v_cvt_pk_bf16_f32 v46, v54, v55
	v_cvt_pk_bf16_f32 v47, v52, v53
	global_store_dwordx4 v[36:37], v[44:47], off
	v_pk_mul_f32 v[48:49], v[48:49], v[62:63] op_sel_hi:[1,0]
	v_cmp_lt_i32_e32 vcc, s8, v32
	v_pk_mul_f32 v[44:45], v[60:61], v[62:63] op_sel_hi:[1,0]
	v_pk_mul_f32 v[46:47], v[50:51], v[62:63] op_sel_hi:[1,0]
	v_pk_mul_f32 v[50:51], v[58:59], v[62:63] op_sel_hi:[1,0]
	v_pk_fma_f32 v[44:45], v[24:25], v[44:45], v[28:29]
	v_pk_fma_f32 v[46:47], v[26:27], v[46:47], v[30:31]
	v_pk_fma_f32 v[50:51], v[16:17], v[50:51], v[20:21]
	v_pk_fma_f32 v[48:49], v[18:19], v[48:49], v[22:23]
	v_cvt_pk_bf16_f32 v44, v44, v45
	v_cvt_pk_bf16_f32 v45, v46, v47
	v_cvt_pk_bf16_f32 v46, v50, v51
	v_cvt_pk_bf16_f32 v47, v48, v49
	s_or_b64 s[42:43], vcc, s[42:43]
	global_store_dwordx4 v[36:37], v[44:47], off offset:1024
	s_andn2_b64 exec, exec, s[42:43]
	s_cbranch_execnz .LBB0_1027

; DI unsigned pack2(float a, float b) { f32x2_t v = {a, b}; return __builtin_bit_cast(unsigned, __builtin_convertvector(v, bf16x2_t)); }
; DI float lo2f(unsigned v) { return __uint_as_float(v << 16); }
; DI float hi2f(unsigned v) { return __uint_as_float(v & 0xffff0000u); }
; DI float wave_sum(float v) { for (int o = 32; o >= 1; o >>= 1) v += __shfl_xor(v, o); return v; }
; DI void ln_phase(int wvs, bf16_t* HB, const float* __restrict__ g, const float* __restrict__ bta, float* fout, bool dostore = true) {
;     ...
;   for (int row = blockIdx.x * 8 + w; row < MTOT; row += gridDim.x * 8) {
;     bf16_t* p = HB + (size_t)row * 1024;
;     float v[16];
;     float s = 0.f;
; #pragma unroll
;     for (int i = 0; i < 2; ++i) {
;       const u32x4 raw = *(const u32x4*)(p + i * 512 + lane * 8);
; #pragma unroll
;       for (int j = 0; j < 4; ++j) { v[i * 8 + 2 * j] = lo2f(raw[j]); v[i * 8 + 2 * j + 1] = hi2f(raw[j]); }
;     }
; #pragma unroll
;     for (int i = 0; i < 16; ++i) s += v[i];
;     const float mean = wave_sum(s) * (1.f / 1024.f);
;     float q = 0.f;
; #pragma unroll
;     for (int i = 0; i < 16; ++i) { v[i] -= mean; q += v[i] * v[i]; }
;     const float rstd = rsqrtf(wave_sum(q) * (1.f / 1024.f) + 1e-5f);
; #pragma unroll
;     for (int i = 0; i < 2; ++i) {
;       const int c = i * 512 + lane * 8;
;       const float4 g0 = *(const float4*)(g + c), g1 = *(const float4*)(g + c + 4), b0 = *(const float4*)(bta + c), b1 = *(const float4*)(bta + c + 4);
;       float o[8];
;       o[0] = v[i * 8 + 0] * rstd * g0.x + b0.x; o[1] = v[i * 8 + 1] * rstd * g0.y + b0.y; o[2] = v[i * 8 + 2] * rstd * g0.z + b0.z; o[3] = v[i * 8 + 3] * rstd * g0.w + b0.w;
;       o[4] = v[i * 8 + 4] * rstd * g1.x + b1.x; o[5] = v[i * 8 + 5] * rstd * g1.y + b1.y; o[6] = v[i * 8 + 6] * rstd * g1.z + b1.z; o[7] = v[i * 8 + 7] * rstd * g1.w + b1.w;
;       if (dostore) {
;         u32x4 pk; pk[0] = pack2(o[0], o[1]); pk[1] = pack2(o[2], o[3]); pk[2] = pack2(o[4], o[5]); pk[3] = pack2(o[6], o[7]);
;         *(u32x4*)(p + c) = pk;
;         if (fout) {
;           *(float4*)(fout + (size_t)row * 1024 + c) = make_float4(o[0], o[1], o[2], o[3]);
;           *(float4*)(fout + (size_t)row * 1024 + c + 4) = make_float4(o[4], o[5], o[6], o[7]);
;         }
;       }
.LBB0_1445:
	v_ashrrev_i32_e32 v41, 31, v40
	v_lshlrev_b64 v[32:33], 11, v[40:41]
	v_lshl_add_u64 v[46:47], v[44:45], 0, v[32:33]
	global_load_dwordx4 v[32:35], v[46:47], off
	global_load_dwordx4 v[36:39], v[46:47], off offset:1024
	v_lshlrev_b64 v[48:49], 12, v[40:41]
	v_readlane_b32 s6, v253, 1
	v_readlane_b32 s7, v253, 2
	v_lshl_add_u64 v[48:49], s[10:11], 0, v[48:49]
	v_lshlrev_b32_e32 v128, 2, v42
	s_waitcnt vmcnt(1)
	v_lshlrev_b32_e32 v52, 16, v32
	v_and_b32_e32 v53, 0xffff0000, v32
	v_add_f32_e32 v32, 0, v52
	v_add_f32_e32 v41, v32, v53
	v_lshlrev_b32_e32 v32, 16, v33
	v_and_b32_e32 v33, 0xffff0000, v33
	v_add_f32_e32 v41, v41, v32
	v_add_f32_e32 v41, v41, v33
	v_lshlrev_b32_e32 v56, 16, v34
	v_and_b32_e32 v57, 0xffff0000, v34
	v_add_f32_e32 v34, v41, v56
	v_add_f32_e32 v41, v34, v57
	v_lshlrev_b32_e32 v34, 16, v35
	v_and_b32_e32 v35, 0xffff0000, v35
	v_add_f32_e32 v41, v41, v34
	s_waitcnt vmcnt(0)
	v_lshlrev_b32_e32 v50, 16, v36
	v_add_f32_e32 v41, v41, v35
	v_and_b32_e32 v51, 0xffff0000, v36
	v_add_f32_e32 v41, v41, v50
	v_lshlrev_b32_e32 v36, 16, v37
	v_add_f32_e32 v41, v41, v51
	v_and_b32_e32 v37, 0xffff0000, v37
	v_add_f32_e32 v41, v41, v36
	v_lshlrev_b32_e32 v54, 16, v38
	v_add_f32_e32 v41, v41, v37
	v_and_b32_e32 v55, 0xffff0000, v38
	v_add_f32_e32 v41, v41, v54
	v_lshlrev_b32_e32 v38, 16, v39
	v_add_f32_e32 v41, v41, v55
	v_and_b32_e32 v39, 0xffff0000, v39
	v_add_f32_e32 v41, v41, v38
	v_add_f32_e32 v41, v41, v39
	s_nop 1
	v_add_f32_dpp v41, v41, v41 quad_perm:[1,0,3,2] row_mask:0xf bank_mask:0xf
	s_nop 1
	v_add_f32_dpp v41, v41, v41 quad_perm:[2,3,0,1] row_mask:0xf bank_mask:0xf
	s_nop 1
	v_add_f32_dpp v41, v41, v41 row_half_mirror row_mask:0xf bank_mask:0xf
	s_nop 1
	v_add_f32_dpp v41, v41, v41 row_mirror row_mask:0xf bank_mask:0xf
	v_mov_b32_e32 v58, v41
	s_nop 1
	v_permlane16_swap_b32_e32 v58, v41
	v_add_f32_e32 v41, v41, v58
	v_mov_b32_e32 v58, v41
	s_nop 1
	v_permlane32_swap_b32_e32 v58, v41
	v_add_f32_e32 v41, v41, v58
	v_mul_f32_e32 v58, 0x3a800000, v41
	v_pk_add_f32 v[66:67], v[52:53], v[58:59] op_sel_hi:[1,0] neg_lo:[0,1] neg_hi:[0,1]
	v_pk_add_f32 v[32:33], v[32:33], v[58:59] op_sel_hi:[1,0] neg_lo:[0,1] neg_hi:[0,1]
	v_pk_mul_f32 v[68:69], v[66:67], v[66:67]
	v_pk_mul_f32 v[70:71], v[32:33], v[32:33]
	v_add_f32_e32 v41, v68, v69
	v_pk_add_f32 v[72:73], v[56:57], v[58:59] op_sel_hi:[1,0] neg_lo:[0,1] neg_hi:[0,1]
	v_add_f32_e32 v41, v70, v41
	v_pk_mul_f32 v[74:75], v[72:73], v[72:73]
	v_add_f32_e32 v41, v71, v41
	v_pk_add_f32 v[34:35], v[34:35], v[58:59] op_sel_hi:[1,0] neg_lo:[0,1] neg_hi:[0,1]
	v_add_f32_e32 v41, v74, v41
	v_pk_mul_f32 v[76:77], v[34:35], v[34:35]
	v_add_f32_e32 v41, v75, v41
	v_pk_add_f32 v[50:51], v[50:51], v[58:59] op_sel_hi:[1,0] neg_lo:[0,1] neg_hi:[0,1]
	v_add_f32_e32 v41, v76, v41
	v_pk_mul_f32 v[78:79], v[50:51], v[50:51]
	v_add_f32_e32 v41, v77, v41
	v_pk_add_f32 v[52:53], v[36:37], v[58:59] op_sel_hi:[1,0] neg_lo:[0,1] neg_hi:[0,1]
	v_add_f32_e32 v41, v78, v41
	v_pk_mul_f32 v[36:37], v[52:53], v[52:53]
	v_add_f32_e32 v41, v79, v41
	v_pk_add_f32 v[54:55], v[54:55], v[58:59] op_sel_hi:[1,0] neg_lo:[0,1] neg_hi:[0,1]
	v_add_f32_e32 v36, v36, v41
	v_pk_mul_f32 v[80:81], v[54:55], v[54:55]
	v_add_f32_e32 v36, v37, v36
	v_pk_add_f32 v[56:57], v[38:39], v[58:59] op_sel_hi:[1,0] neg_lo:[0,1] neg_hi:[0,1]
	v_add_f32_e32 v36, v80, v36
	v_pk_mul_f32 v[38:39], v[56:57], v[56:57]
	v_add_f32_e32 v36, v81, v36
	v_add_f32_e32 v36, v38, v36
	v_add_f32_e32 v36, v39, v36
	ds_bpermute_b32 v37, v43, v36
	v_cndmask_b32_e64 v41, 0, 1, s[6:7]
	v_cmp_ne_u32_e64 s[40:41], 1, v41
	s_waitcnt lgkmcnt(0)
	v_add_f32_e32 v36, v36, v37
	ds_bpermute_b32 v37, v60, v36
	s_waitcnt lgkmcnt(0)
	v_add_f32_e32 v36, v36, v37
	ds_bpermute_b32 v37, v61, v36
	s_waitcnt lgkmcnt(0)
	v_add_f32_e32 v36, v36, v37
	ds_bpermute_b32 v37, v62, v36
	s_waitcnt lgkmcnt(0)
	v_add_f32_e32 v36, v36, v37
	ds_bpermute_b32 v37, v63, v36
	s_waitcnt lgkmcnt(0)
	v_add_f32_e32 v36, v36, v37
	ds_bpermute_b32 v37, v64, v36
	s_waitcnt lgkmcnt(0)
	v_add_f32_e32 v36, v36, v37
	v_fmamk_f32 v36, v36, 0x3a800000, v177
	v_cmp_gt_f32_e32 vcc, s75, v36
	v_mul_f32_e32 v37, 0x4b800000, v36
	s_nop 0
	v_cndmask_b32_e32 v36, v36, v37, vcc
	v_rsq_f32_e32 v36, v36
	s_nop 0
	v_mul_f32_e32 v37, 0x45800000, v36
	v_cndmask_b32_e32 v58, v36, v37, vcc
	v_pk_mul_f32 v[32:33], v[32:33], v[58:59] op_sel_hi:[1,0]
	v_pk_mul_f32 v[36:37], v[66:67], v[58:59] op_sel_hi:[1,0]
	v_pk_fma_f32 v[38:39], v[10:11], v[32:33], v[14:15]
	v_pk_mul_f32 v[32:33], v[72:73], v[58:59] op_sel_hi:[1,0]
	v_pk_mul_f32 v[34:35], v[34:35], v[58:59] op_sel_hi:[1,0]
	v_pk_fma_f32 v[36:37], v[8:9], v[36:37], v[12:13]
	v_pk_fma_f32 v[32:33], v[0:1], v[32:33], v[4:5]
	v_pk_fma_f32 v[34:35], v[2:3], v[34:35], v[6:7]
	v_cvt_pk_bf16_f32 v66, v36, v37
	v_cvt_pk_bf16_f32 v67, v38, v39
	v_cvt_pk_bf16_f32 v68, v32, v33
	v_cvt_pk_bf16_f32 v69, v34, v35
	s_andn2_b64 vcc, exec, s[6:7]
	s_cbranch_vccnz .LBB0_1447
	s_nop 0
	v_lshl_add_u64 v[66:67], v[48:49], 0, v[128:129]
	global_store_dwordx4 v[66:67], v[36:39], off
	global_store_dwordx4 v[66:67], v[32:35], off offset:16
